# combo7: combo6 + attention work-queue claim atomic returns into the nclaim register and is waited with a counted vmcnt at the unit end instead of vmcnt(0) inside the last tile-pair staging block
# baseline (speedup 1.0000x reference)
; template <int TYPE> __device__ __forceinline__ void attn_unit(const AttnCtx& C, int b, int h, int qb, LAS unsigned char* lds, int tid_in, unsigned* counter) {
;     ...
;                 if (pass == NPASS - 1 && t + 2 >= t1 && tid == 0) nclaim = atomicAdd(counter, 1u);
;                 __syncthreads();
.LBB0_389:
	s_cmp_ge_i32 s0, s10
	s_cselect_b64 s[0:1], -1, 0
	s_and_b64 s[0:1], s[0:1], s[84:85]
	s_and_saveexec_b64 s[4:5], s[0:1]
	s_cbranch_execz .LBB0_393
	s_mov_b64 s[8:9], exec
	v_mbcnt_lo_u32_b32 v32, s8, 0
	v_mbcnt_hi_u32_b32 v32, s9, v32
	v_cmp_eq_u32_e32 vcc, 0, v32
	s_and_saveexec_b64 s[0:1], vcc
	s_cbranch_execz .LBB0_392
	s_bcnt1_i32_b64 s8, s[8:9]
	v_mov_b32_e32 v33, s8
	v_readlane_b32 s8, v251, 17
	v_readlane_b32 s9, v251, 18
	s_nop 4
	global_atomic_add v164, v145, v33, s[8:9] sc0
.LBB0_392:
	s_or_b64 exec, exec, s[0:1]
.LBB0_393:
	s_or_b64 exec, exec, s[4:5]
	s_waitcnt lgkmcnt(0)
	s_barrier

; template <int TYPE> __device__ __forceinline__ void attn_unit(const AttnCtx& C, int b, int h, int qb, LAS unsigned char* lds, int tid_in, unsigned* counter) {
;     ...
;                 if (pass == NPASS - 1 && t + 2 >= t1 && tid == 0) nclaim = atomicAdd(counter, 1u);
;                 __syncthreads();
.LBB0_415:
	s_cmp_ge_u32 s92, s7
	s_cselect_b64 s[0:1], -1, 0
	s_and_b64 s[0:1], s[84:85], s[0:1]
	s_and_saveexec_b64 s[94:95], s[0:1]
	s_cbranch_execz .LBB0_419
	s_mov_b64 s[96:97], exec
	v_mbcnt_lo_u32_b32 v48, s96, 0
	v_mbcnt_hi_u32_b32 v48, s97, v48
	v_cmp_eq_u32_e32 vcc, 0, v48
	s_and_saveexec_b64 s[0:1], vcc
	s_cbranch_execz .LBB0_418
	s_bcnt1_i32_b64 s96, s[96:97]
	v_mov_b32_e32 v49, s96
	v_readlane_b32 s96, v251, 17
	v_readlane_b32 s97, v251, 18
	s_nop 4
	global_atomic_add v164, v145, v49, s[96:97] sc0
.LBB0_418:
	s_or_b64 exec, exec, s[0:1]
.LBB0_419:
	s_or_b64 exec, exec, s[94:95]
	s_waitcnt lgkmcnt(0)
	s_barrier

; template <int TYPE> __device__ __forceinline__ void attn_unit(const AttnCtx& C, int b, int h, int qb, LAS unsigned char* lds, int tid_in, unsigned* counter) {
;     ...
;                 if (pass == NPASS - 1 && t + 2 >= t1 && tid == 0) nclaim = atomicAdd(counter, 1u);
;                 __syncthreads();
.LBB0_449:
	s_cmp_ge_i32 s0, s93
	s_cselect_b64 s[0:1], -1, 0
	s_and_b64 s[0:1], s[0:1], s[84:85]
	s_and_saveexec_b64 s[8:9], s[0:1]
	s_cbranch_execz .LBB0_453
	s_mov_b64 s[0:1], exec
	v_mbcnt_lo_u32_b32 v64, s0, 0
	v_mbcnt_hi_u32_b32 v64, s1, v64
	v_cmp_eq_u32_e32 vcc, 0, v64
	s_and_saveexec_b64 s[10:11], vcc
	s_cbranch_execz .LBB0_452
	s_bcnt1_i32_b64 s0, s[0:1]
	v_mov_b32_e32 v65, s0
	v_readlane_b32 s0, v251, 17
	v_readlane_b32 s1, v251, 18
	s_nop 4
	global_atomic_add v164, v145, v65, s[0:1] sc0
.LBB0_452:
	s_or_b64 exec, exec, s[10:11]
.LBB0_453:
	s_or_b64 exec, exec, s[8:9]
	s_waitcnt lgkmcnt(0)
	s_barrier

; #define LAS __attribute__((address_space(3)))
; template <int TYPE> __device__ __forceinline__ void attn_unit(const AttnCtx& C, int b, int h, int qb, LAS unsigned char* lds, int tid_in, unsigned* counter) {
;     ...
;     if (tid == 0) ((LAS unsigned*)(lds + AL_U))[0] = nclaim;
.LBB0_460:
	s_and_saveexec_b64 s[0:1], s[84:85]
	s_xor_b64 s[0:1], exec, s[0:1]
	s_cbranch_execz .LBB0_350
	s_waitcnt vmcnt(32)
	ds_write_b32 v154, v164
	s_branch .LBB0_350

; template <int TYPE> __device__ __forceinline__ void attn_unit(const AttnCtx& C, int b, int h, int qb, LAS unsigned char* lds, int tid_in, unsigned* counter) {
;     ...
;                 if (pass == NPASS - 1 && t + 2 >= t1 && tid == 0) nclaim = atomicAdd(counter, 1u);
;                 __syncthreads();
.LBB0_1315:
	s_cmp_ge_i32 s0, s11
	s_cselect_b64 s[0:1], -1, 0
	s_and_b64 s[2:3], s[0:1], s[8:9]
	s_and_saveexec_b64 s[0:1], s[2:3]
	s_cbranch_execz .LBB0_1319
	s_mov_b64 s[2:3], exec
	v_mbcnt_lo_u32_b32 v32, s2, 0
	v_mbcnt_hi_u32_b32 v32, s3, v32
	v_cmp_eq_u32_e32 vcc, 0, v32
	s_and_saveexec_b64 s[4:5], vcc
	s_cbranch_execz .LBB0_1318
	s_bcnt1_i32_b64 s2, s[2:3]
	v_mov_b32_e32 v33, s2
	v_readlane_b32 s2, v251, 17
	v_readlane_b32 s3, v251, 18
	s_nop 4
	global_atomic_add v164, v145, v33, s[2:3] sc0
.LBB0_1318:
	s_or_b64 exec, exec, s[4:5]
.LBB0_1319:
	s_or_b64 exec, exec, s[0:1]
	s_waitcnt lgkmcnt(0)
	s_barrier

; template <int TYPE> __device__ __forceinline__ void attn_unit(const AttnCtx& C, int b, int h, int qb, LAS unsigned char* lds, int tid_in, unsigned* counter) {
;     ...
;                 if (pass == NPASS - 1 && t + 2 >= t1 && tid == 0) nclaim = atomicAdd(counter, 1u);
;                 __syncthreads();
.LBB0_1341:
	s_cmp_ge_u32 s87, s81
	s_cselect_b64 s[0:1], -1, 0
	s_and_b64 s[2:3], s[8:9], s[0:1]
	s_and_saveexec_b64 s[0:1], s[2:3]
	s_cbranch_execz .LBB0_1345
	s_mov_b64 s[2:3], exec
	v_mbcnt_lo_u32_b32 v48, s2, 0
	v_mbcnt_hi_u32_b32 v48, s3, v48
	v_cmp_eq_u32_e32 vcc, 0, v48
	s_and_saveexec_b64 s[90:91], vcc
	s_cbranch_execz .LBB0_1344
	s_bcnt1_i32_b64 s2, s[2:3]
	v_mov_b32_e32 v49, s2
	v_readlane_b32 s2, v251, 17
	v_readlane_b32 s3, v251, 18
	s_nop 4
	global_atomic_add v164, v145, v49, s[2:3] sc0
.LBB0_1344:
	s_or_b64 exec, exec, s[90:91]
.LBB0_1345:
	s_or_b64 exec, exec, s[0:1]
	s_waitcnt lgkmcnt(0)
	s_barrier

; template <int TYPE> __device__ __forceinline__ void attn_unit(const AttnCtx& C, int b, int h, int qb, LAS unsigned char* lds, int tid_in, unsigned* counter) {
;     ...
;                 if (pass == NPASS - 1 && t + 2 >= t1 && tid == 0) nclaim = atomicAdd(counter, 1u);
;                 __syncthreads();
.LBB0_1375:
	s_cmp_ge_i32 s0, s33
	s_cselect_b64 s[0:1], -1, 0
	s_and_b64 s[2:3], s[0:1], s[8:9]
	s_and_saveexec_b64 s[0:1], s[2:3]
	s_cbranch_execz .LBB0_1379
	s_mov_b64 s[2:3], exec
	v_mbcnt_lo_u32_b32 v64, s2, 0
	v_mbcnt_hi_u32_b32 v64, s3, v64
	v_cmp_eq_u32_e32 vcc, 0, v64
	s_and_saveexec_b64 s[4:5], vcc
	s_cbranch_execz .LBB0_1378
	s_bcnt1_i32_b64 s2, s[2:3]
	v_mov_b32_e32 v65, s2
	v_readlane_b32 s2, v251, 17
	v_readlane_b32 s3, v251, 18
	s_nop 4
	global_atomic_add v164, v145, v65, s[2:3] sc0
.LBB0_1378:
	s_or_b64 exec, exec, s[4:5]
.LBB0_1379:
	s_or_b64 exec, exec, s[0:1]
	s_waitcnt lgkmcnt(0)
	s_barrier

; #define LAS __attribute__((address_space(3)))
; template <int TYPE> __device__ __forceinline__ void attn_unit(const AttnCtx& C, int b, int h, int qb, LAS unsigned char* lds, int tid_in, unsigned* counter) {
;     ...
;     if (tid == 0) ((LAS unsigned*)(lds + AL_U))[0] = nclaim;
.LBB0_1386:
	s_and_saveexec_b64 s[0:1], s[8:9]
	s_xor_b64 s[0:1], exec, s[0:1]
	s_cbranch_execz .LBB0_1276
	s_waitcnt vmcnt(32)
	ds_write_b32 v154, v164
	s_branch .LBB0_1276
